# lever 7 instruction selection: NA local-tile scale+bias fmacs take the log2e/8 constant from s17 instead of a 32-bit literal (4-byte instead of 8-byte encodings)
# speedup vs baseline: 1.0056x; 1.0002x over previous
.Lna_rot_body:
	s_and_b32 s15, s14, 64
	v_add_u32_e32 v66, s24, v148
	s_cmp_gt_u32 s24, 8
	s_cselect_b64 s[10:11], -1, 0
	s_cmp_lt_u32 s24, 9
	v_cmp_gt_u32_e32 vcc, 8, v66
	s_movk_i32 s13, 0x1800
	s_cselect_b64 s[28:29], -1, 0
	s_or_b64 s[2:3], s[10:11], vcc
	s_and_saveexec_b64 s[38:39], s[2:3]
	s_cbranch_execz .LBB0_337
	v_or_b32_e32 v66, s15, v138
	v_mad_u32_u24 v82, v66, s16, v145
	s_cmp_lt_u32 s24, 9
	s_cbranch_scc0 .Lna_ctx_tile
	s_bitcmp1_b32 s100, 6
	s_cbranch_scc1 .Lna_loc_h1
	ds_read_b128 v[164:167], v82 offset:0
	ds_read_b128 v[168:171], v82 offset:64
	ds_read_b128 v[172:175], v82 offset:2304
	ds_read_b128 v[176:179], v82 offset:2368
	ds_read_b128 v[180:183], v82 offset:4608
	ds_read_b128 v[184:187], v82 offset:4672
	ds_read2_b32 v[224:225], v147 offset0:16 offset1:17
	ds_read2_b32 v[226:227], v147 offset0:18 offset1:19
	ds_read2_b32 v[228:229], v147 offset0:32 offset1:33
	ds_read2_b32 v[230:231], v147 offset0:34 offset1:35
	v_mov_b32_e32 v158, 0xf149f2ca
	s_waitcnt lgkmcnt(9)
	v_mfma_f32_16x16x32_bf16 v[90:93], v[164:167], v[38:41], 0
	s_waitcnt lgkmcnt(8)
	v_mfma_f32_16x16x32_bf16 v[90:93], v[168:171], v[34:37], v[90:93]
	s_waitcnt lgkmcnt(7)
	v_mfma_f32_16x16x32_bf16 v[94:97], v[172:175], v[38:41], 0
	s_waitcnt lgkmcnt(6)
	v_mfma_f32_16x16x32_bf16 v[94:97], v[176:179], v[34:37], v[94:97]
	ds_read2_b32 v[232:233], v147 offset0:0 offset1:1
	ds_read2_b32 v[234:235], v147 offset0:2 offset1:3
	ds_read2_b32 v[236:237], v147 offset0:16 offset1:17
	ds_read2_b32 v[238:239], v147 offset0:18 offset1:19
	ds_read2_b32 v[240:241], v147 offset0:32 offset1:33
	ds_read2_b32 v[242:243], v147 offset0:34 offset1:35
	v_mfma_f32_16x16x32_bf16 v[98:101], v[164:167], v[46:49], 0
	v_or_b32_e32 v160, s15, v135
	v_mul_u32_u24_e32 v160, 0x48, v160
	v_lshl_add_u32 v160, v160, 1, v136
	s_waitcnt lgkmcnt(6)
	v_fmac_f32_e32 v224, s17, v90
	v_mfma_f32_16x16x32_bf16 v[98:101], v[168:171], v[42:45], v[98:101]
	v_fmac_f32_e32 v225, s17, v91
	v_fmac_f32_e32 v226, s17, v92
	v_fmac_f32_e32 v227, s17, v93
	v_fmac_f32_e32 v228, s17, v94
	v_mfma_f32_16x16x32_bf16 v[102:105], v[172:175], v[46:49], 0
	v_fmac_f32_e32 v229, s17, v95
	v_fmac_f32_e32 v230, s17, v96
	v_fmac_f32_e32 v231, s17, v97
	v_cndmask_b32_e64 v224, v158, v224, s[40:41]
	v_mfma_f32_16x16x32_bf16 v[102:105], v[176:179], v[42:45], v[102:105]
	v_cndmask_b32_e64 v225, v158, v225, s[42:43]
	v_cndmask_b32_e64 v226, v158, v226, s[44:45]
	v_cndmask_b32_e64 v227, v158, v227, s[46:47]
	v_cndmask_b32_e64 v228, v158, v228, s[48:49]
	v_mfma_f32_16x16x32_bf16 v[106:109], v[180:183], v[46:49], 0
	v_cndmask_b32_e64 v229, v158, v229, s[50:51]
	v_cndmask_b32_e64 v230, v158, v230, s[52:53]
	v_cndmask_b32_e64 v231, v158, v231, s[54:55]
	v_max3_f32 v150, v224, s18, v225
	v_mfma_f32_16x16x32_bf16 v[106:109], v[184:187], v[42:45], v[106:109]
	v_max3_f32 v150, v150, v226, v227
	v_max3_f32 v150, v150, v228, v229
	v_max3_f32 v150, v150, v230, v231
	s_waitcnt lgkmcnt(0)
	ds_read_b64_tr_b16 v[164:165], v160 offset:18432
	ds_read_b64_tr_b16 v[166:167], v160 offset:20736
	ds_read_b64_tr_b16 v[168:169], v160 offset:18464
	ds_read_b64_tr_b16 v[170:171], v160 offset:20768
	ds_read_b64_tr_b16 v[172:173], v160 offset:23040
	ds_read_b64_tr_b16 v[174:175], v160 offset:25344
	ds_read_b64_tr_b16 v[176:177], v160 offset:23072
	ds_read_b64_tr_b16 v[178:179], v160 offset:25376
	v_fmac_f32_e32 v232, s17, v98
	v_fmac_f32_e32 v233, s17, v99
	v_fmac_f32_e32 v234, s17, v100
	v_fmac_f32_e32 v235, s17, v101
	v_fmac_f32_e32 v236, s17, v102
	v_fmac_f32_e32 v237, s17, v103
	v_fmac_f32_e32 v238, s17, v104
	v_fmac_f32_e32 v239, s17, v105
	v_fmac_f32_e32 v240, s17, v106
	v_fmac_f32_e32 v241, s17, v107
	v_fmac_f32_e32 v242, s17, v108
	v_fmac_f32_e32 v243, s17, v109
	v_cndmask_b32_e64 v232, v158, v232, s[72:73]
	v_cndmask_b32_e64 v233, v158, v233, s[74:75]
	v_cndmask_b32_e64 v234, v158, v234, s[76:77]
	v_cndmask_b32_e64 v235, v158, v235, s[78:79]
	v_cndmask_b32_e64 v236, v158, v236, s[80:81]
	v_cndmask_b32_e64 v237, v158, v237, s[82:83]
	v_cndmask_b32_e64 v238, v158, v238, s[84:85]
	v_cndmask_b32_e64 v239, v158, v239, s[86:87]
	v_cndmask_b32_e64 v240, v158, v240, s[88:89]
	v_cndmask_b32_e64 v241, v158, v241, s[90:91]
	v_cndmask_b32_e64 v242, v158, v242, s[92:93]
	v_cndmask_b32_e64 v243, v158, v243, s[4:5]
	v_max3_f32 v151, v232, s18, v233
	v_max3_f32 v151, v151, v234, v235
	v_max3_f32 v151, v151, v236, v237
	v_max3_f32 v151, v151, v238, v239
	v_max3_f32 v151, v151, v240, v241
	v_max3_f32 v151, v151, v242, v243
	v_mov_b32_e32 v152, v150
	v_mov_b32_e32 v153, v151
	s_nop 0
	v_permlane16_swap_b32_e32 v152, v150
	v_permlane16_swap_b32_e32 v153, v151
	v_max_f32_e32 v150, v150, v152
	v_max_f32_e32 v151, v151, v153
	v_mov_b32_e32 v152, v150
	v_mov_b32_e32 v153, v151
	s_nop 0
	v_permlane32_swap_b32_e32 v152, v150
	v_permlane32_swap_b32_e32 v153, v151
	v_max_f32_e32 v150, v150, v152
	v_max_f32_e32 v151, v151, v153
	v_add_f32_e32 v110, 0x41000000, v144
	v_cmp_gt_f32_e32 vcc, v150, v110
	s_cbranch_vccz .Lna_l0_keep0
	v_max_f32_e32 v244, v144, v150
	v_sub_f32_e32 v110, v144, v244
	v_exp_f32_e32 v110, v110
	v_mov_b32_e32 v144, v244
	v_mul_f32_e32 v140, v140, v110
	v_pk_mul_f32 v[18:19], v[18:19], v[110:111] op_sel_hi:[1,0]
	v_pk_mul_f32 v[20:21], v[20:21], v[110:111] op_sel_hi:[1,0]
	v_pk_mul_f32 v[22:23], v[22:23], v[110:111] op_sel_hi:[1,0]
	v_pk_mul_f32 v[24:25], v[24:25], v[110:111] op_sel_hi:[1,0]
	v_pk_mul_f32 v[10:11], v[10:11], v[110:111] op_sel_hi:[1,0]
	v_pk_mul_f32 v[12:13], v[12:13], v[110:111] op_sel_hi:[1,0]
	v_pk_mul_f32 v[2:3], v[2:3], v[110:111] op_sel_hi:[1,0]
	v_pk_mul_f32 v[4:5], v[4:5], v[110:111] op_sel_hi:[1,0]

.Lna_loc_h1:
	ds_read_b128 v[164:167], v82 offset:2304
	ds_read_b128 v[168:171], v82 offset:2368
	ds_read_b128 v[172:175], v82 offset:4608
	ds_read_b128 v[176:179], v82 offset:4672
	ds_read_b128 v[180:183], v82 offset:6912
	ds_read_b128 v[184:187], v82 offset:6976
	ds_read2_b32 v[224:225], v147 offset0:32 offset1:33
	ds_read2_b32 v[226:227], v147 offset0:34 offset1:35
	ds_read2_b32 v[228:229], v147 offset0:48 offset1:49
	ds_read2_b32 v[230:231], v147 offset0:50 offset1:51
	ds_read2_b32 v[232:233], v147 offset0:64 offset1:65
	ds_read2_b32 v[234:235], v147 offset0:66 offset1:67
	v_mov_b32_e32 v158, 0xf149f2ca
	s_waitcnt lgkmcnt(11)
	v_mfma_f32_16x16x32_bf16 v[90:93], v[164:167], v[38:41], 0
	s_waitcnt lgkmcnt(10)
	v_mfma_f32_16x16x32_bf16 v[90:93], v[168:171], v[34:37], v[90:93]
	s_waitcnt lgkmcnt(9)
	v_mfma_f32_16x16x32_bf16 v[94:97], v[172:175], v[38:41], 0
	s_waitcnt lgkmcnt(8)
	v_mfma_f32_16x16x32_bf16 v[94:97], v[176:179], v[34:37], v[94:97]
	s_waitcnt lgkmcnt(7)
	v_mfma_f32_16x16x32_bf16 v[98:101], v[180:183], v[38:41], 0
	s_waitcnt lgkmcnt(6)
	v_mfma_f32_16x16x32_bf16 v[98:101], v[184:187], v[34:37], v[98:101]
	ds_read2_b32 v[236:237], v147 offset0:32 offset1:33
	ds_read2_b32 v[238:239], v147 offset0:34 offset1:35
	ds_read2_b32 v[240:241], v147 offset0:48 offset1:49
	ds_read2_b32 v[242:243], v147 offset0:50 offset1:51
	v_mfma_f32_16x16x32_bf16 v[102:105], v[172:175], v[46:49], 0
	v_or_b32_e32 v160, s15, v135
	v_mul_u32_u24_e32 v160, 0x48, v160
	v_lshl_add_u32 v160, v160, 1, v136
	s_waitcnt lgkmcnt(4)
	v_fmac_f32_e32 v224, s17, v90
	v_fmac_f32_e32 v225, s17, v91
	v_fmac_f32_e32 v226, s17, v92
	v_fmac_f32_e32 v227, s17, v93
	v_fmac_f32_e32 v228, s17, v94
	v_fmac_f32_e32 v229, s17, v95
	v_mfma_f32_16x16x32_bf16 v[102:105], v[176:179], v[42:45], v[102:105]
	v_fmac_f32_e32 v230, s17, v96
	v_fmac_f32_e32 v231, s17, v97
	v_fmac_f32_e32 v232, s17, v98
	v_fmac_f32_e32 v233, s17, v99
	v_fmac_f32_e32 v234, s17, v100
	v_fmac_f32_e32 v235, s17, v101
	v_cndmask_b32_e64 v224, v158, v224, s[48:49]
	v_cndmask_b32_e64 v225, v158, v225, s[50:51]
	v_cndmask_b32_e64 v226, v158, v226, s[52:53]
	v_mfma_f32_16x16x32_bf16 v[106:109], v[180:183], v[46:49], 0
	v_cndmask_b32_e64 v227, v158, v227, s[54:55]
	v_cndmask_b32_e64 v228, v158, v228, s[56:57]
	v_cndmask_b32_e64 v229, v158, v229, s[58:59]
	v_cndmask_b32_e64 v230, v158, v230, s[60:61]
	v_cndmask_b32_e64 v231, v158, v231, s[62:63]
	v_cndmask_b32_e64 v232, v158, v232, s[64:65]
	v_cndmask_b32_e64 v233, v158, v233, s[66:67]
	v_cndmask_b32_e64 v234, v158, v234, s[68:69]
	v_cndmask_b32_e64 v235, v158, v235, s[70:71]
	v_mfma_f32_16x16x32_bf16 v[106:109], v[184:187], v[42:45], v[106:109]
	v_max3_f32 v150, v224, s18, v225
	v_max3_f32 v150, v150, v226, v227
	v_max3_f32 v150, v150, v228, v229
	v_max3_f32 v150, v150, v230, v231
	v_max3_f32 v150, v150, v232, v233
	v_max3_f32 v150, v150, v234, v235
	s_waitcnt lgkmcnt(0)
	ds_read_b64_tr_b16 v[164:165], v160 offset:18432
	ds_read_b64_tr_b16 v[166:167], v160 offset:20736
	ds_read_b64_tr_b16 v[168:169], v160 offset:18464
	ds_read_b64_tr_b16 v[170:171], v160 offset:20768
	ds_read_b64_tr_b16 v[172:173], v160 offset:23040
	ds_read_b64_tr_b16 v[174:175], v160 offset:25344
	ds_read_b64_tr_b16 v[176:177], v160 offset:23072
	ds_read_b64_tr_b16 v[178:179], v160 offset:25376
	v_fmac_f32_e32 v236, s17, v102
	v_fmac_f32_e32 v237, s17, v103
	v_fmac_f32_e32 v238, s17, v104
	v_fmac_f32_e32 v239, s17, v105
	v_fmac_f32_e32 v240, s17, v106
	v_fmac_f32_e32 v241, s17, v107
	v_fmac_f32_e32 v242, s17, v108
	v_fmac_f32_e32 v243, s17, v109
	v_cndmask_b32_e64 v236, v158, v236, s[88:89]
	v_cndmask_b32_e64 v237, v158, v237, s[90:91]
	v_cndmask_b32_e64 v238, v158, v238, s[92:93]
	v_cndmask_b32_e64 v239, v158, v239, s[4:5]
	v_cndmask_b32_e64 v240, v158, v240, s[94:95]
	v_cndmask_b32_e64 v241, v158, v241, s[6:7]
	v_cndmask_b32_e64 v242, v158, v242, s[8:9]
	v_cndmask_b32_e64 v243, v158, v243, s[96:97]
	v_max3_f32 v151, v236, s18, v237
	v_max3_f32 v151, v151, v238, v239
	v_max3_f32 v151, v151, v240, v241
	v_max3_f32 v151, v151, v242, v243
	v_mov_b32_e32 v152, v150
	v_mov_b32_e32 v153, v151
	s_nop 0
	v_permlane16_swap_b32_e32 v152, v150
	v_permlane16_swap_b32_e32 v153, v151
	v_max_f32_e32 v150, v150, v152
	v_max_f32_e32 v151, v151, v153
	v_mov_b32_e32 v152, v150
	v_mov_b32_e32 v153, v151
	s_nop 0
	v_permlane32_swap_b32_e32 v152, v150
	v_permlane32_swap_b32_e32 v153, v151
	v_max_f32_e32 v150, v150, v152
	v_max_f32_e32 v151, v151, v153
	v_add_f32_e32 v110, 0x41000000, v144
	v_cmp_gt_f32_e32 vcc, v150, v110
	s_cbranch_vccz .Lna_l1_keep0
	v_max_f32_e32 v244, v144, v150
	v_sub_f32_e32 v110, v144, v244
	v_exp_f32_e32 v110, v110
	v_mov_b32_e32 v144, v244
	v_mul_f32_e32 v140, v140, v110
	v_pk_mul_f32 v[18:19], v[18:19], v[110:111] op_sel_hi:[1,0]
	v_pk_mul_f32 v[20:21], v[20:21], v[110:111] op_sel_hi:[1,0]
	v_pk_mul_f32 v[22:23], v[22:23], v[110:111] op_sel_hi:[1,0]
	v_pk_mul_f32 v[24:25], v[24:25], v[110:111] op_sel_hi:[1,0]
	v_pk_mul_f32 v[10:11], v[10:11], v[110:111] op_sel_hi:[1,0]
	v_pk_mul_f32 v[12:13], v[12:13], v[110:111] op_sel_hi:[1,0]
	v_pk_mul_f32 v[2:3], v[2:3], v[110:111] op_sel_hi:[1,0]
	v_pk_mul_f32 v[4:5], v[4:5], v[110:111] op_sel_hi:[1,0]
